# combo6 + mixer-A/B running-output rescale skipped for lanes whose alpha is exactly 1.0 (bit-identical; uses s[100:101], next_free_sgpr 102)
# baseline (speedup 1.0000x reference)
; #define LAS __attribute__((address_space(3)))
; template <int MODE> ...
;     ...
;             for (int ks = 0; ks < 4; ++ks) {
;                 const bf16x8 a0 = *(const LAS bf16x8*)(kb + 32 * ks);
;                 const bf16x8 a1 = *(const LAS bf16x8*)(kb + 32 * KP + 32 * ks);
;                 s0 = __builtin_amdgcn_mfma_f32_32x32x16_bf16(a0, qf[ks], s0, 0, 0, 0);
;                 s1 = __builtin_amdgcn_mfma_f32_32x32x16_bf16(a1, qf[ks], s1, 0, 0, 0);
;             }
;             if (MODE == 0) {
;                 const LAS float* bh = bias + (w >> 1) * 384 + (T * 64 - qpos + 192 + 8 * h);
; #pragma unroll
;                 for (int i = 0; i < 16; ++i) { const int o_ = 16 * (i >> 3) + (i & 7);
;                     s0[i] = s0[i] * C2 + bh[o_]; s1[i] = s1[i] * C2 + bh[o_ + 32]; }
;             } else if (MODE == 1) {
;                 const LAS float* bh = bias + (T - grow + 7) * 128 + (63 - (32 * (w & 1) + r) + 8 * h);
; #pragma unroll
;                 for (int i = 0; i < 16; ++i) { const int o_ = 16 * (i >> 3) + (i & 7);
;                     s0[i] = (s0[i] * C2 + bh[o_]) + pen0[i]; s1[i] = (s1[i] * C2 + bh[o_ + 32]) + pen1[i]; }
;             }
;             float mx = fmaxf(s0[0], s1[0]);
; #pragma unroll
;             for (int i = 1; i < 16; ++i) mx = fmaxf(mx, fmaxf(s0[i], s1[i]));
;             mx = fmaxf(mx, __shfl_xor(mx, 32));
;             const float mnew = fmaxf(m, mx);
;             const float alpha = __builtin_amdgcn_exp2f(m - mnew);
;             m = mnew;
;             float ps = 0.f;
; #pragma unroll
;             for (int i = 0; i < 16; ++i) { s0[i] = __builtin_amdgcn_exp2f(s0[i] - mnew); s1[i] = __builtin_amdgcn_exp2f(s1[i] - mnew); ps += s0[i] + s1[i]; }
;             l = l * alpha + ps;
; #pragma unroll
;             for (int i = 0; i < 16; ++i) { o0[i] *= alpha; o1[i] *= alpha; }
;             u32x4 pw[4];
; #pragma unroll
;             for (int q = 0; q < 4; ++q) { pw[0][q] = pk_bf16(s0[2 * q], s0[2 * q + 1]); pw[1][q] = pk_bf16(s0[8 + 2 * q], s0[8 + 2 * q + 1]);
;                                           pw[2][q] = pk_bf16(s1[2 * q], s1[2 * q + 1]); pw[3][q] = pk_bf16(s1[8 + 2 * q], s1[8 + 2 * q + 1]); }
;             const LAS unsigned char* vb = lds + ATT_V + buf * ATT_TILE + r * KP + 16 * h;
; #pragma unroll
;             for (int ks = 0; ks < 4; ++ks) {
;                 const bf16x8 a0 = *(const LAS bf16x8*)(vb + 32 * ks);
.LBB0_294:
	s_and_b32 s4, s11, 1
	s_mul_i32 s5, s4, 0x2400
	v_add_u32_e32 v189, s5, v128
	ds_read_b128 v[32:35], v189
	ds_read_b128 v[190:193], v189 offset:32
	ds_read_b128 v[48:51], v189 offset:4608
	ds_read_b128 v[194:197], v189 offset:4640
	s_andn2_b64 vcc, exec, s[20:21]
	s_waitcnt lgkmcnt(3)
	v_mfma_f32_32x32x16_bf16 v[32:47], v[32:35], v[64:67], 0
	s_waitcnt lgkmcnt(1)
	v_mfma_f32_32x32x16_bf16 v[48:63], v[48:51], v[64:67], 0
	v_mfma_f32_32x32x16_bf16 v[32:47], v[190:193], v[68:71], v[32:47]
	s_waitcnt lgkmcnt(0)
	v_mfma_f32_32x32x16_bf16 v[48:63], v[194:197], v[68:71], v[48:63]
	ds_read_b128 v[190:193], v189 offset:64
	ds_read_b128 v[194:197], v189 offset:96
	s_waitcnt lgkmcnt(1)
	v_mfma_f32_32x32x16_bf16 v[32:47], v[190:193], v[72:75], v[32:47]
	ds_read_b128 v[190:193], v189 offset:4672
	ds_read_b128 v[200:203], v189 offset:4704
	s_waitcnt lgkmcnt(1)
	v_mfma_f32_32x32x16_bf16 v[48:63], v[190:193], v[72:75], v[48:63]
	ds_read2_b32 v[190:191], v187 offset1:1
	v_mfma_f32_32x32x16_bf16 v[32:47], v[194:197], v[76:79], v[32:47]
	ds_read2_b32 v[192:193], v187 offset0:2 offset1:3
	ds_read2_b32 v[194:195], v187 offset0:4 offset1:5
	ds_read2_b32 v[196:197], v187 offset0:6 offset1:7
	ds_read2_b32 v[204:205], v187 offset0:32 offset1:33
	ds_read2_b32 v[206:207], v187 offset0:34 offset1:35
	ds_read2_b32 v[210:211], v187 offset0:36 offset1:37
	ds_read2_b32 v[212:213], v187 offset0:38 offset1:39
	s_waitcnt lgkmcnt(7)
	s_nop 3
	v_fmamk_f32 v189, v32, 0x3e38aa3b, v190
	v_mfma_f32_32x32x16_bf16 v[48:63], v[200:203], v[76:79], v[48:63]
	v_fmac_f32_e32 v191, 0x3e38aa3b, v33
	s_waitcnt lgkmcnt(6)
	v_fmac_f32_e32 v193, 0x3e38aa3b, v35
	s_waitcnt lgkmcnt(5)
	v_fmac_f32_e32 v195, 0x3e38aa3b, v37
	s_waitcnt lgkmcnt(4)
	v_fmac_f32_e32 v197, 0x3e38aa3b, v39
	s_waitcnt lgkmcnt(3)
	s_nop 3
	v_fmac_f32_e32 v205, 0x3e38aa3b, v49
	v_fmamk_f32 v49, v34, 0x3e38aa3b, v192
	s_waitcnt lgkmcnt(2)
	v_fmac_f32_e32 v207, 0x3e38aa3b, v51
	v_fmamk_f32 v51, v36, 0x3e38aa3b, v194
	s_waitcnt lgkmcnt(1)
	v_fmac_f32_e32 v211, 0x3e38aa3b, v53
	v_fmamk_f32 v53, v38, 0x3e38aa3b, v196
	s_waitcnt lgkmcnt(0)
	v_fmamk_f32 v190, v54, 0x3e38aa3b, v212
	v_fmac_f32_e32 v213, 0x3e38aa3b, v55
	ds_read2_b32 v[54:55], v187 offset0:16 offset1:17
	ds_read2_b32 v[36:37], v187 offset0:48 offset1:49
	ds_read2_b32 v[200:201], v187 offset0:18 offset1:19
	ds_read2_b32 v[202:203], v187 offset0:20 offset1:21
	ds_read2_b32 v[214:215], v187 offset0:22 offset1:23
	ds_read2_b32 v[38:39], v187 offset0:50 offset1:51
	ds_read2_b32 v[34:35], v187 offset0:52 offset1:53
	ds_read2_b32 v[32:33], v187 offset0:54 offset1:55
	v_fmamk_f32 v48, v48, 0x3e38aa3b, v204
	v_fmamk_f32 v50, v50, 0x3e38aa3b, v206
	v_fmamk_f32 v52, v52, 0x3e38aa3b, v210
	s_waitcnt lgkmcnt(6)
	v_fmamk_f32 v196, v56, 0x3e38aa3b, v36
	s_waitcnt lgkmcnt(0)
	v_fmamk_f32 v210, v62, 0x3e38aa3b, v32
	v_max_f32_e32 v32, v191, v205
	v_fmamk_f32 v208, v60, 0x3e38aa3b, v34
	v_max3_f32 v32, v189, v48, v32
	v_max_f32_e32 v34, v49, v50
	v_max_f32_e32 v36, v193, v207
	v_max3_f32 v32, v32, v34, v36
	v_max_f32_e32 v34, v51, v52
	v_max_f32_e32 v36, v195, v211
	v_fmamk_f32 v54, v40, 0x3e38aa3b, v54
	v_fmac_f32_e32 v55, 0x3e38aa3b, v41
	v_fmac_f32_e32 v37, 0x3e38aa3b, v57
	v_max3_f32 v32, v32, v34, v36
	v_max_f32_e32 v34, v53, v190
	v_max_f32_e32 v36, v197, v213
	v_fmamk_f32 v56, v42, 0x3e38aa3b, v200
	v_fmamk_f32 v198, v58, 0x3e38aa3b, v38
	v_fmac_f32_e32 v201, 0x3e38aa3b, v43
	v_fmac_f32_e32 v39, 0x3e38aa3b, v59
	v_max3_f32 v32, v32, v34, v36
	v_max_f32_e32 v34, v54, v196
	v_max_f32_e32 v36, v55, v37
	v_fmamk_f32 v58, v44, 0x3e38aa3b, v202
	v_fmac_f32_e32 v203, 0x3e38aa3b, v45
	v_fmac_f32_e32 v35, 0x3e38aa3b, v61
	v_max3_f32 v32, v32, v34, v36
	v_max_f32_e32 v34, v56, v198
	v_max_f32_e32 v36, v201, v39
	v_fmamk_f32 v60, v46, 0x3e38aa3b, v214
	v_fmac_f32_e32 v215, 0x3e38aa3b, v47
	v_fmac_f32_e32 v33, 0x3e38aa3b, v63
	v_max3_f32 v32, v32, v34, v36
	v_max_f32_e32 v34, v58, v208
	v_max_f32_e32 v36, v203, v35
	v_max3_f32 v32, v32, v34, v36
	v_max_f32_e32 v34, v60, v210
	v_max_f32_e32 v36, v215, v33
	v_max3_f32 v32, v32, v34, v36
	ds_bpermute_b32 v34, v185, v32
	s_waitcnt lgkmcnt(0)
	v_max3_f32 v34, v188, v32, v34
	v_sub_f32_e32 v42, v49, v34
	v_sub_f32_e32 v49, v211, v34
	v_add_u32_e32 v211, s5, v186
	v_sub_f32_e32 v32, v188, v34
	v_sub_f32_e32 v36, v189, v34
	v_sub_f32_e32 v40, v191, v34
	v_sub_f32_e32 v46, v51, v34
	v_sub_f32_e32 v51, v190, v34
	ds_read_b128 v[188:191], v211 offset:18432
	v_sub_f32_e32 v38, v48, v34
	v_sub_f32_e32 v43, v50, v34
	v_sub_f32_e32 v44, v193, v34
	v_sub_f32_e32 v47, v52, v34
	v_sub_f32_e32 v48, v195, v34
	v_sub_f32_e32 v50, v53, v34
	v_sub_f32_e32 v52, v197, v34
	v_exp_f32_e32 v32, v32
	v_exp_f32_e32 v36, v36
	v_exp_f32_e32 v40, v40
	v_exp_f32_e32 v42, v42
	v_exp_f32_e32 v44, v44
	v_exp_f32_e32 v46, v46
	v_exp_f32_e32 v48, v48
	v_exp_f32_e32 v50, v50
	v_exp_f32_e32 v52, v52
	v_sub_f32_e32 v57, v201, v34
	v_sub_f32_e32 v59, v203, v34
	ds_read_b128 v[192:195], v211 offset:23040
	ds_read_b128 v[200:203], v211 offset:18464
	v_sub_f32_e32 v197, v60, v34
	v_cvt_pk_bf16_f32 v60, v36, v40
	v_cvt_pk_bf16_f32 v61, v42, v44
	v_cvt_pk_bf16_f32 v62, v46, v48
	v_cvt_pk_bf16_f32 v63, v50, v52
	v_cmp_neq_f32_e64 s[100:101], 1.0, v32
	s_nop 1
	s_mov_b64 exec, s[100:101]
	s_cbranch_execz .Lal_a1
	v_pk_mul_f32 v[14:15], v[14:15], v[32:33] op_sel_hi:[1,0]
	v_pk_mul_f32 v[12:13], v[12:13], v[32:33] op_sel_hi:[1,0]
	v_pk_mul_f32 v[10:11], v[10:11], v[32:33] op_sel_hi:[1,0]
	v_pk_mul_f32 v[8:9], v[8:9], v[32:33] op_sel_hi:[1,0]
	v_pk_mul_f32 v[6:7], v[6:7], v[32:33] op_sel_hi:[1,0]
	v_pk_mul_f32 v[4:5], v[4:5], v[32:33] op_sel_hi:[1,0]
	v_pk_mul_f32 v[2:3], v[2:3], v[32:33] op_sel_hi:[1,0]
	v_pk_mul_f32 v[0:1], v[0:1], v[32:33] op_sel_hi:[1,0]
	v_pk_mul_f32 v[30:31], v[30:31], v[32:33] op_sel_hi:[1,0]
	v_pk_mul_f32 v[28:29], v[28:29], v[32:33] op_sel_hi:[1,0]
; #define LAS __attribute__((address_space(3)))
; __device__ __forceinline__ unsigned pk_bf16(float lo, float hi) { return pg8::cvt_pk_bf16(lo, hi); }
; template <int MODE> ...
;     ...
;             for (int i = 0; i < 16; ++i) { s0[i] = __builtin_amdgcn_exp2f(s0[i] - mnew); s1[i] = __builtin_amdgcn_exp2f(s1[i] - mnew); ps += s0[i] + s1[i]; }
;             l = l * alpha + ps;
; #pragma unroll
;             for (int i = 0; i < 16; ++i) { o0[i] *= alpha; o1[i] *= alpha; }
;             u32x4 pw[4];
; #pragma unroll
;             for (int q = 0; q < 4; ++q) { pw[0][q] = pk_bf16(s0[2 * q], s0[2 * q + 1]); pw[1][q] = pk_bf16(s0[8 + 2 * q], s0[8 + 2 * q + 1]);
;                                           pw[2][q] = pk_bf16(s1[2 * q], s1[2 * q + 1]); pw[3][q] = pk_bf16(s1[8 + 2 * q], s1[8 + 2 * q + 1]); }
;             const LAS unsigned char* vb = lds + ATT_V + buf * ATT_TILE + r * KP + 16 * h;
; #pragma unroll
;             for (int ks = 0; ks < 4; ++ks) {
;                 const bf16x8 a0 = *(const LAS bf16x8*)(vb + 32 * ks);
;                 const bf16x8 a1 = *(const LAS bf16x8*)(vb + 32 * KP + 32 * ks);
;                 const bf16x8 pf = __builtin_bit_cast(bf16x8, pw[ks]);
;                 o0 = __builtin_amdgcn_mfma_f32_32x32x16_bf16(a0, pf, o0, 0, 0, 0);
;                 o1 = __builtin_amdgcn_mfma_f32_32x32x16_bf16(a1, pf, o1, 0, 0, 0);
;             }
;         }
;         if (it + 1 < nT) { *(LAS u32x4*)(lds + ATT_K + (buf ^ 1) * ATT_TILE + sdst) = kreg; *(LAS u32x4*)(lds + ATT_V + (buf ^ 1) * ATT_TILE + sdst) = vreg; }
.Lal_a1:
	s_mov_b64 exec, -1
	s_waitcnt lgkmcnt(2)
	v_mfma_f32_32x32x16_bf16 v[0:15], v[188:191], v[60:63], v[0:15]
	s_mov_b64 exec, s[100:101]
	s_cbranch_execz .Lal_a2
	v_mul_f32_e64 v26, v26, v32
	v_mul_f32_e64 v27, v27, v32
	v_mul_f32_e64 v24, v24, v32
	v_mul_f32_e64 v25, v25, v32
	v_mul_f32_e64 v22, v22, v32
	v_mul_f32_e64 v23, v23, v32
	v_pk_mul_f32 v[20:21], v[20:21], v[32:33] op_sel_hi:[1,0]
	v_pk_mul_f32 v[18:19], v[18:19], v[32:33] op_sel_hi:[1,0]
	v_pk_mul_f32 v[16:17], v[16:17], v[32:33] op_sel_hi:[1,0]
.Lal_a2:
	s_mov_b64 exec, -1
	ds_read_b128 v[188:191], v211 offset:23072
	v_sub_f32_e32 v54, v54, v34
	v_sub_f32_e32 v55, v55, v34
	v_sub_f32_e32 v56, v56, v34
	v_sub_f32_e32 v58, v58, v34
	s_waitcnt lgkmcnt(2)
	v_mfma_f32_32x32x16_bf16 v[16:31], v[192:195], v[60:63], v[16:31]
	v_sub_f32_e32 v61, v215, v34
	v_exp_f32_e32 v54, v54
	v_exp_f32_e32 v55, v55
	v_exp_f32_e32 v56, v56
	v_exp_f32_e32 v57, v57
	v_exp_f32_e32 v58, v58
	v_exp_f32_e32 v59, v59
	v_exp_f32_e32 v60, v197
	v_exp_f32_e32 v61, v61
	v_cvt_pk_bf16_f32 v192, v54, v55
	v_cvt_pk_bf16_f32 v193, v56, v57
	v_cvt_pk_bf16_f32 v194, v58, v59
	v_cvt_pk_bf16_f32 v195, v60, v61
	v_sub_f32_e32 v41, v205, v34
	v_sub_f32_e32 v45, v207, v34
	s_waitcnt lgkmcnt(1)
	v_mfma_f32_32x32x16_bf16 v[0:15], v[200:203], v[192:195], v[0:15]
	ds_read_b128 v[200:203], v211 offset:18496
	v_sub_f32_e32 v53, v213, v34
	v_exp_f32_e32 v38, v38
	v_exp_f32_e32 v41, v41
	v_exp_f32_e32 v43, v43
	v_exp_f32_e32 v45, v45
	v_exp_f32_e32 v47, v47
	s_waitcnt lgkmcnt(1)
	v_mfma_f32_32x32x16_bf16 v[16:31], v[188:191], v[192:195], v[16:31]
	v_exp_f32_e32 v49, v49
	v_exp_f32_e32 v51, v51
	v_exp_f32_e32 v53, v53
	v_sub_f32_e32 v62, v196, v34
	ds_read_b128 v[194:197], v211 offset:23104
	ds_read_b128 v[204:207], v211 offset:18528
	v_cvt_pk_bf16_f32 v190, v38, v41
	v_cvt_pk_bf16_f32 v191, v43, v45
	v_cvt_pk_bf16_f32 v192, v47, v49
	v_cvt_pk_bf16_f32 v193, v51, v53
	v_sub_f32_e32 v37, v37, v34
	v_sub_f32_e32 v63, v198, v34
	s_waitcnt lgkmcnt(2)
	v_mfma_f32_32x32x16_bf16 v[0:15], v[200:203], v[190:193], v[0:15]
	ds_read_b128 v[200:203], v211 offset:23136
	v_sub_f32_e32 v39, v39, v34
	v_sub_f32_e32 v188, v208, v34
	v_sub_f32_e32 v35, v35, v34
	v_sub_f32_e32 v189, v210, v34
	v_sub_f32_e32 v33, v33, v34
	v_exp_f32_e32 v62, v62
	s_waitcnt lgkmcnt(2)
	v_mfma_f32_32x32x16_bf16 v[16:31], v[194:197], v[190:193], v[16:31]
	v_exp_f32_e32 v37, v37
	v_exp_f32_e32 v63, v63
	v_exp_f32_e32 v39, v39
	v_exp_f32_e32 v188, v188
	v_exp_f32_e32 v35, v35
	v_exp_f32_e32 v189, v189
	v_exp_f32_e32 v33, v33
	v_cvt_pk_bf16_f32 v190, v62, v37
	v_cvt_pk_bf16_f32 v191, v63, v39
	v_cvt_pk_bf16_f32 v192, v188, v35
	v_cvt_pk_bf16_f32 v193, v189, v33
	s_waitcnt lgkmcnt(1)
	s_nop 0
	v_mfma_f32_32x32x16_bf16 v[0:15], v[204:207], v[190:193], v[0:15]
	s_waitcnt lgkmcnt(0)
	v_mfma_f32_32x32x16_bf16 v[16:31], v[200:203], v[190:193], v[16:31]
	s_cbranch_vccnz .LBB0_296
	s_xor_b32 s4, s4, 1
	s_mulk_i32 s4, 0x2400
	v_add_u32_e32 v190, s4, v183
	s_waitcnt vmcnt(1)
	ds_write_b128 v190, v[80:83]
	s_waitcnt vmcnt(0)
	ds_write_b128 v190, v[84:87] offset:18432

; #define LAS __attribute__((address_space(3)))
; __device__ __forceinline__ unsigned pk_bf16(float lo, float hi) { return pg8::cvt_pk_bf16(lo, hi); }
; __device__ __forceinline__ void attn_b_unit(LAS unsigned char* lds, const bf16_t* proj, const bf16_t* vt, bf16_t* obuf, int b, int hk, int blk, const float* btab, unsigned long long* sg, bool build_lut, CP WP, int wlayer, int wbase) {
;     ...
;         if (T >= wlo && T <= whi) {
;             const LAS unsigned char* kb = lds + ATT_K + buf * ATT_TILE + (kc0 + pr) * KP + 16 * h;
;             f32x16 s0;
; #pragma unroll
;             for (int i = 0; i < 16; ++i) s0[i] = 0.f;
; #pragma unroll
;             for (int ks = 0; ks < 4; ++ks) s0 = __builtin_amdgcn_mfma_f32_32x32x16_bf16(*(const LAS bf16x8*)(kb + 32 * ks), qf[ks], s0, 0, 0, 0);
;             const int dr = (T >= rsq && T < rsq + 8) ? T - rq + 7 : 15;
;             const LAS float* bh = bias + dr * 128 + (kc0 + 8 * h - c + 63);
; #pragma unroll
;             for (int i = 0; i < 16; ++i) s0[i] = (s0[i] * C2 + bh[16 * (i >> 3) + (i & 7)]) + pen[i];
;             float mx = s0[0];
; #pragma unroll
;             for (int i = 1; i < 16; ++i) mx = fmaxf(mx, s0[i]);
;             mx = fmaxf(mx, __shfl_xor(mx, 32));
;             const float mnew = fmaxf(mrun, mx);
;             const float alpha = __builtin_amdgcn_exp2f(mrun - mnew);
;             mrun = mnew;
;             float ps = 0.f;
; #pragma unroll
;             for (int i = 0; i < 16; ++i) { s0[i] = __builtin_amdgcn_exp2f(s0[i] - mnew); ps += s0[i]; }
;             l = l * alpha + ps;
; #pragma unroll
;             for (int i = 0; i < 16; ++i) { o0[i] *= alpha; o1[i] *= alpha; }
;             u32x4 pw[2];
; #pragma unroll
;             for (int q = 0; q < 4; ++q) { pw[0][q] = pk_bf16(s0[2 * q], s0[2 * q + 1]); pw[1][q] = pk_bf16(s0[8 + 2 * q], s0[8 + 2 * q + 1]); }
;             const LAS unsigned char* vb = lds + ATT_V + buf * ATT_TILE + r * KP + 2 * kc0 + 16 * h;
; #pragma unroll
;             for (int ks = 0; ks < 2; ++ks) {
;                 const bf16x8 a0 = *(const LAS bf16x8*)(vb + 32 * ks), a1 = *(const LAS bf16x8*)(vb + 32 * KP + 32 * ks);
;                 const bf16x8 pf = __builtin_bit_cast(bf16x8, pw[ks]);
;                 o0 = __builtin_amdgcn_mfma_f32_32x32x16_bf16(a0, pf, o0, 0, 0, 0);
;                 o1 = __builtin_amdgcn_mfma_f32_32x32x16_bf16(a1, pf, o1, 0, 0, 0);
;             }
.LBB0_379:
	s_add_i32 s6, s51, s20
	s_and_b32 s10, s20, 1
	s_cmp_gt_u32 s4, s6
	s_cselect_b64 s[30:31], -1, 0
	s_and_b64 s[30:31], s[22:23], s[30:31]
	s_cmp_gt_u32 s6, s21
	s_cselect_b64 s[34:35], -1, 0
	s_or_b64 s[30:31], s[30:31], s[34:35]
	s_and_b64 vcc, exec, s[30:31]
	s_cbranch_vccnz .LBB0_381
	s_mul_i32 s11, s10, 0x2400
	v_add_u32_e32 v193, s11, v187
	ds_read_b128 v[32:35], v193
	ds_read_b128 v[194:197], v193 offset:32
	v_cmp_ge_u32_e32 vcc, s6, v186
	v_cmp_lt_u32_e64 s[6:7], s6, v188
	s_and_b64 vcc, vcc, s[6:7]
	s_waitcnt lgkmcnt(1)
	v_mfma_f32_32x32x16_bf16 v[32:47], v[32:35], v[48:51], 0
	s_waitcnt lgkmcnt(0)
	v_mfma_f32_32x32x16_bf16 v[32:47], v[194:197], v[52:55], v[32:47]
	ds_read_b128 v[194:197], v193 offset:64
	s_waitcnt lgkmcnt(0)
	v_mfma_f32_32x32x16_bf16 v[32:47], v[194:197], v[56:59], v[32:47]
	ds_read_b128 v[194:197], v193 offset:96
	v_cndmask_b32_e32 v193, v225, v191, vcc
	v_lshl_add_u32 v193, v193, 2, v189
	s_waitcnt lgkmcnt(0)
	v_mfma_f32_32x32x16_bf16 v[32:47], v[194:197], v[60:63], v[32:47]
	v_add_u32_e32 v194, 0x90fc, v193
	ds_read2_b32 v[194:195], v194 offset1:1
	s_waitcnt lgkmcnt(0)
	s_nop 8
	v_fmamk_f32 v32, v32, 0x3e38aa3b, v194
	v_add_f32_e32 v194, v157, v32
	v_add_u32_e32 v32, 0x9104, v193
	v_fmac_f32_e32 v195, 0x3e38aa3b, v33
	ds_read2_b32 v[32:33], v32 offset1:1
	v_add_f32_e32 v195, v159, v195
	s_waitcnt lgkmcnt(0)
	v_fmamk_f32 v32, v34, 0x3e38aa3b, v32
	v_add_f32_e32 v34, v160, v32
	v_fmac_f32_e32 v33, 0x3e38aa3b, v35
	v_add_u32_e32 v32, 0x910c, v193
	v_add_f32_e32 v35, v161, v33
	ds_read2_b32 v[32:33], v32 offset1:1
	s_waitcnt lgkmcnt(0)
	v_fmamk_f32 v32, v36, 0x3e38aa3b, v32
	v_add_f32_e32 v196, v162, v32
	v_fmac_f32_e32 v33, 0x3e38aa3b, v37
	v_add_u32_e32 v32, 0x9114, v193
	v_add_f32_e32 v37, v163, v33
	ds_read2_b32 v[32:33], v32 offset1:1
	v_max_f32_e32 v36, v194, v195
	v_max3_f32 v36, v36, v34, v35
	v_max3_f32 v36, v36, v196, v37
	s_waitcnt lgkmcnt(0)
	v_fmamk_f32 v32, v38, 0x3e38aa3b, v32
	v_add_f32_e32 v38, v164, v32
	v_fmac_f32_e32 v33, 0x3e38aa3b, v39
	v_add_u32_e32 v32, 0x913c, v193
	v_add_f32_e32 v39, v165, v33
	ds_read2_b32 v[32:33], v32 offset1:1
	v_max3_f32 v36, v36, v38, v39
	s_waitcnt lgkmcnt(0)
	v_fmamk_f32 v32, v40, 0x3e38aa3b, v32
	v_add_f32_e32 v40, v166, v32
	v_fmac_f32_e32 v33, 0x3e38aa3b, v41
	v_add_u32_e32 v32, 0x9144, v193
	v_add_f32_e32 v41, v167, v33
	ds_read2_b32 v[32:33], v32 offset1:1
	v_max3_f32 v36, v36, v40, v41
	s_waitcnt lgkmcnt(0)
	v_fmamk_f32 v32, v42, 0x3e38aa3b, v32
	v_add_f32_e32 v42, v168, v32
	v_fmac_f32_e32 v33, 0x3e38aa3b, v43
	v_add_u32_e32 v32, 0x914c, v193
	v_add_f32_e32 v43, v169, v33
	ds_read2_b32 v[32:33], v32 offset1:1
	v_max3_f32 v36, v36, v42, v43
	s_waitcnt lgkmcnt(0)
	v_fmamk_f32 v32, v44, 0x3e38aa3b, v32
	v_add_f32_e32 v44, v182, v32
	v_fmac_f32_e32 v33, 0x3e38aa3b, v45
	v_add_u32_e32 v32, 0x9154, v193
	v_add_f32_e32 v45, v183, v33
	ds_read2_b32 v[32:33], v32 offset1:1
	v_max3_f32 v36, v36, v44, v45
	s_waitcnt lgkmcnt(0)
	v_fmamk_f32 v32, v46, 0x3e38aa3b, v32
	v_fmac_f32_e32 v33, 0x3e38aa3b, v47
	v_add_f32_e32 v32, v184, v32
	v_add_f32_e32 v33, v185, v33
	v_max3_f32 v36, v36, v32, v33
	ds_bpermute_b32 v46, v158, v36
	s_waitcnt lgkmcnt(0)
	v_max3_f32 v46, v192, v36, v46
	v_sub_f32_e32 v38, v38, v46
	v_sub_f32_e32 v47, v194, v46
	v_exp_f32_e32 v194, v38
	v_sub_f32_e32 v38, v39, v46
	v_sub_f32_e32 v36, v192, v46
	v_sub_f32_e32 v192, v195, v46
	v_exp_f32_e32 v195, v38
	v_sub_f32_e32 v38, v40, v46
	v_exp_f32_e32 v39, v38
	v_sub_f32_e32 v38, v41, v46
	v_exp_f32_e32 v47, v47
	v_exp_f32_e32 v40, v38
	v_sub_f32_e32 v38, v42, v46
	v_exp_f32_e32 v192, v192
	v_sub_f32_e32 v34, v34, v46
	v_exp_f32_e32 v41, v38
	v_sub_f32_e32 v38, v43, v46
	v_exp_f32_e32 v34, v34
	v_sub_f32_e32 v35, v35, v46
	v_exp_f32_e32 v42, v38
	v_sub_f32_e32 v38, v44, v46
	v_sub_f32_e32 v32, v32, v46
	v_exp_f32_e32 v35, v35
	v_sub_f32_e32 v193, v196, v46
	v_exp_f32_e32 v43, v38
	v_sub_f32_e32 v38, v45, v46
	v_exp_f32_e32 v45, v32
	v_sub_f32_e32 v32, v33, v46
	v_exp_f32_e32 v193, v193
	v_sub_f32_e32 v37, v37, v46
	v_exp_f32_e32 v196, v32
	v_add_f32_e32 v32, 0, v47
	v_exp_f32_e32 v37, v37
	v_add_f32_e32 v32, v192, v32
	v_add_f32_e32 v32, v34, v32
	v_add_f32_e32 v32, v35, v32
	v_add_f32_e32 v32, v193, v32
	v_add_f32_e32 v32, v37, v32
	v_add_f32_e32 v32, v194, v32
	v_add_f32_e32 v32, v195, v32
	v_add_f32_e32 v32, v39, v32
	v_exp_f32_e32 v44, v38
	v_add_f32_e32 v32, v40, v32
	v_add_f32_e32 v32, v41, v32
	v_exp_f32_e32 v36, v36
	v_add_f32_e32 v32, v42, v32
	v_add_f32_e32 v32, v43, v32
	v_add_f32_e32 v32, v44, v32
	v_add_f32_e32 v32, v45, v32
	v_add_f32_e32 v197, v196, v32
	v_cvt_pk_bf16_f32 v32, v39, v40
	v_cvt_pk_bf16_f32 v40, v193, v37
	v_cmp_neq_f32_e64 s[100:101], 1.0, v36
	s_nop 1
	s_mov_b64 exec, s[100:101]
	s_cbranch_execz .Lal_b1
	v_pk_mul_f32 v[14:15], v[14:15], v[36:37] op_sel_hi:[1,0]
	v_pk_mul_f32 v[12:13], v[12:13], v[36:37] op_sel_hi:[1,0]
	v_pk_mul_f32 v[10:11], v[10:11], v[36:37] op_sel_hi:[1,0]
	v_pk_mul_f32 v[8:9], v[8:9], v[36:37] op_sel_hi:[1,0]
	v_pk_mul_f32 v[6:7], v[6:7], v[36:37] op_sel_hi:[1,0]
	v_pk_mul_f32 v[4:5], v[4:5], v[36:37] op_sel_hi:[1,0]
	v_pk_mul_f32 v[2:3], v[2:3], v[36:37] op_sel_hi:[1,0]
	v_pk_mul_f32 v[0:1], v[0:1], v[36:37] op_sel_hi:[1,0]
	v_pk_mul_f32 v[30:31], v[30:31], v[36:37] op_sel_hi:[1,0]
	v_pk_mul_f32 v[28:29], v[28:29], v[36:37] op_sel_hi:[1,0]
	v_pk_mul_f32 v[26:27], v[26:27], v[36:37] op_sel_hi:[1,0]
	v_pk_mul_f32 v[24:25], v[24:25], v[36:37] op_sel_hi:[1,0]
	v_pk_mul_f32 v[22:23], v[22:23], v[36:37] op_sel_hi:[1,0]
	v_pk_mul_f32 v[20:21], v[20:21], v[36:37] op_sel_hi:[1,0]
	v_pk_mul_f32 v[18:19], v[18:19], v[36:37] op_sel_hi:[1,0]
	v_pk_mul_f32 v[16:17], v[16:17], v[36:37] op_sel_hi:[1,0]
.Lal_b1:
	s_mov_b64 exec, -1
	v_add_u32_e32 v37, s11, v190
	v_cvt_pk_bf16_f32 v38, v47, v192
	v_cvt_pk_bf16_f32 v39, v34, v35
	v_cvt_pk_bf16_f32 v33, v41, v42
	v_cvt_pk_bf16_f32 v34, v43, v44
	v_cvt_pk_bf16_f32 v41, v194, v195
	v_cvt_pk_bf16_f32 v35, v45, v196
	ds_read_b128 v[42:45], v37 offset:23040
	ds_read_b128 v[192:195], v37 offset:18432
	ds_read_b128 v[200:203], v37 offset:18464
	s_waitcnt lgkmcnt(1)
	v_mfma_f32_32x32x16_bf16 v[0:15], v[192:195], v[38:41], v[0:15]
	v_fmac_f32_e32 v197, v156, v36
	v_mov_b32_e32 v156, v197
	v_mov_b32_e32 v192, v46
	v_mfma_f32_32x32x16_bf16 v[16:31], v[42:45], v[38:41], v[16:31]
	ds_read_b128 v[38:41], v37 offset:23072
	s_waitcnt lgkmcnt(1)
	v_mfma_f32_32x32x16_bf16 v[0:15], v[200:203], v[32:35], v[0:15]
	s_waitcnt lgkmcnt(0)
	v_mfma_f32_32x32x16_bf16 v[16:31], v[38:41], v[32:35], v[16:31]

; __global__ void __launch_bounds__(512, 2) hymba_fwd(Params Parg) {
	.amdhsa_kernel _Z9hymba_fwd6Params
		.amdhsa_group_segment_fixed_size 0
		.amdhsa_private_segment_fixed_size 0
		.amdhsa_kernarg_size 400
		.amdhsa_user_sgpr_count 2
		.amdhsa_user_sgpr_dispatch_ptr 0
		.amdhsa_user_sgpr_queue_ptr 0
		.amdhsa_user_sgpr_kernarg_segment_ptr 1
		.amdhsa_user_sgpr_dispatch_id 0
		.amdhsa_user_sgpr_kernarg_preload_length 0
		.amdhsa_user_sgpr_kernarg_preload_offset 0
		.amdhsa_user_sgpr_private_segment_size 0
		.amdhsa_uses_dynamic_stack 0
		.amdhsa_enable_private_segment 0
		.amdhsa_system_sgpr_workgroup_id_x 1
		.amdhsa_system_sgpr_workgroup_id_y 0
		.amdhsa_system_sgpr_workgroup_id_z 0
		.amdhsa_system_sgpr_workgroup_info 0
		.amdhsa_system_vgpr_workitem_id 2
		.amdhsa_next_free_vgpr 251
		.amdhsa_next_free_sgpr 102
		.amdhsa_accum_offset 252
		.amdhsa_reserve_vcc 1
		.amdhsa_float_round_mode_32 0
		.amdhsa_float_round_mode_16_64 0
		.amdhsa_float_denorm_mode_32 3
		.amdhsa_float_denorm_mode_16_64 3
		.amdhsa_dx10_clamp 1
		.amdhsa_ieee_mode 1
		.amdhsa_fp16_overflow 0
		.amdhsa_tg_split 0
		.amdhsa_exception_fp_ieee_invalid_op 0
		.amdhsa_exception_fp_denorm_src 0
		.amdhsa_exception_fp_ieee_div_zero 0
		.amdhsa_exception_fp_ieee_overflow 0
		.amdhsa_exception_fp_ieee_underflow 0
		.amdhsa_exception_fp_ieee_inexact 0
		.amdhsa_exception_int_div_zero 0
	.end_amdhsa_kernel

; __global__ void __launch_bounds__(512, 2) hymba_fwd(Params Parg) {
;     extern __shared__ __attribute__((aligned(16))) unsigned char lds_raw[];
amdhsa.kernels:
  - .agpr_count:     0
    .args:
      - .offset:         0
        .size:           144
        .value_kind:     by_value
      - .offset:         144
        .size:           4
        .value_kind:     hidden_block_count_x
      - .offset:         148
        .size:           4
        .value_kind:     hidden_block_count_y
      - .offset:         152
        .size:           4
        .value_kind:     hidden_block_count_z
      - .offset:         156
        .size:           2
        .value_kind:     hidden_group_size_x
      - .offset:         158
        .size:           2
        .value_kind:     hidden_group_size_y
      - .offset:         160
        .size:           2
        .value_kind:     hidden_group_size_z
      - .offset:         162
        .size:           2
        .value_kind:     hidden_remainder_x
      - .offset:         164
        .size:           2
        .value_kind:     hidden_remainder_y
      - .offset:         166
        .size:           2
        .value_kind:     hidden_remainder_z
      - .offset:         184
        .size:           8
        .value_kind:     hidden_global_offset_x
      - .offset:         192
        .size:           8
        .value_kind:     hidden_global_offset_y
      - .offset:         200
        .size:           8
        .value_kind:     hidden_global_offset_z
      - .offset:         208
        .size:           2
        .value_kind:     hidden_grid_dims
      - .offset:         232
        .size:           8
        .value_kind:     hidden_multigrid_sync_arg
      - .offset:         264
        .size:           4
        .value_kind:     hidden_dynamic_lds_size
    .group_segment_fixed_size: 0
    .kernarg_segment_align: 8
    .kernarg_segment_size: 400
    .language:       OpenCL C
    .language_version:
      - 2
      - 0
    .max_flat_workgroup_size: 512
    .name:           _Z9hymba_fwd6Params
    .private_segment_fixed_size: 0
    .sgpr_count:     108
    .sgpr_spill_count: 50
    .symbol:         _Z9hymba_fwd6Params.kd
    .uniform_work_group_size: 1
    .uses_dynamic_stack: false
    .vgpr_count:     251
    .vgpr_spill_count: 0
    .wavefront_size: 64
